# v25 plus cumsum gate loads batched (8 in flight) and phase_post next-row loads prefetched one iteration ahead
# speedup vs baseline: 1.0123x; 1.0123x over previous
; DI float softplusf_(float x) { return fmaxf(x, 0.f) + log1pf(__expf(-fabsf(x))); }
; DI int bid_() { return (int)blockIdx.x; }
; DI void phase_cumsum(const Params& p, int j, lptr lds) {
;     ...
;     for (int s = bid_(); s < 64; s += gridDim.x) {
;         const int b = s >> 3, h = s & 7; const float bias = bfg[h];
;         float v[8]; float run = 0.f;
;         for (int e = 0; e < 8; ++e) { const float f = GATE[((size_t)b * SEQ + tid * 8 + e) * 8 + h] + bias; run += -softplusf_(-f); v[e] = run; }
;         float inc = run; const int lane = tid & 63, wv = tid >> 6;
;         for (int d = 1; d < 64; d <<= 1) { const float t = __builtin_bit_cast(float, __builtin_amdgcn_ds_bpermute(((lane - d) & 63) << 2, __builtin_bit_cast(int, inc))); if (lane >= d) inc += t; }
;         __syncthreads();
;         if (lane == 63) lst<float>(lds, wv * 4, inc);
.LBB0_212:
	s_and_b32 s0, s2, 7
	s_lshl_b32 s0, s0, 2
	v_mov_b32_e32 v0, s0
	global_load_dword v23, v0, s[26:27]
	s_and_b32 s0, s11, 7
	s_lshl_b32 s3, s0, 2
	s_ashr_i32 s0, s2, 3
	s_ashr_i32 s1, s0, 31
	s_lshl_b64 s[0:1], s[0:1], 17
	s_or_b32 s0, s0, s3
	v_lshl_add_u64 v[14:15], v[12:13], 0, s[0:1]
	global_load_dword v60, v[14:15], off
	global_load_dword v61, v[14:15], off offset:32
	global_load_dword v62, v[14:15], off offset:64
	global_load_dword v63, v[14:15], off offset:96
	global_load_dword v64, v[14:15], off offset:128
	global_load_dword v65, v[14:15], off offset:160
	global_load_dword v66, v[14:15], off offset:192
	global_load_dword v67, v[14:15], off offset:224
	v_mov_b32_e32 v0, 0
	s_mov_b64 s[92:93], 0
.LBB0_213:
	s_cmp_eq_u32 s92, 7
	v_lshl_add_u64 v[14:15], v[14:15], 0, 32
	s_waitcnt vmcnt(0)
	v_mov_b32_e32 v24, v60
	v_mov_b32_e32 v60, v61
	v_mov_b32_e32 v61, v62
	v_mov_b32_e32 v62, v63
	v_mov_b32_e32 v63, v64
	v_mov_b32_e32 v64, v65
	v_mov_b32_e32 v65, v66
	v_mov_b32_e32 v66, v67
	v_add_f32_e32 v24, v23, v24
	v_max_f32_e64 v38, -v24, 0
	v_mul_f32_e64 v24, |v24|, s73
	v_exp_f32_e32 v39, v24
	s_nop 0
	v_add_f32_e32 v26, 1.0, v39
	v_add_f32_e32 v27, -1.0, v26
	v_frexp_mant_f32_e32 v28, v26
	v_cvt_f64_f32_e32 v[24:25], v26
	v_sub_f32_e32 v29, v27, v26
	v_frexp_exp_i32_f64_e32 v24, v[24:25]
	v_cmp_gt_f32_e64 s[0:1], s74, v28
	v_sub_f32_e32 v27, v39, v27
	v_add_f32_e32 v25, 1.0, v29
	v_subbrev_co_u32_e64 v24, s[0:1], 0, v24, s[0:1]
	v_add_f32_e32 v25, v27, v25
	v_sub_u32_e32 v27, 0, v24
	v_ldexp_f32 v26, v26, v27
	v_add_f32_e32 v28, -1.0, v26
	v_add_f32_e32 v29, 1.0, v26
	v_ldexp_f32 v25, v25, v27
	v_add_f32_e32 v27, 1.0, v28
	v_add_f32_e32 v30, -1.0, v29
	v_sub_f32_e32 v27, v26, v27
	v_sub_f32_e32 v26, v26, v30
	v_add_f32_e32 v30, v25, v27
	v_add_f32_e32 v25, v25, v26
	v_add_f32_e32 v32, v29, v25
	v_rcp_f32_e32 v33, v32
	v_add_f32_e32 v27, v28, v30
	v_sub_f32_e32 v28, v27, v28
	v_sub_f32_e32 v26, v32, v29
	v_mul_f32_e32 v35, v27, v33
	v_sub_f32_e32 v34, v30, v28
	v_mul_f32_e32 v28, v32, v35
	v_sub_f32_e32 v25, v25, v26
	v_fma_f32 v30, v35, v32, -v28
	v_fmac_f32_e32 v30, v35, v25
	v_add_f32_e32 v26, v28, v30
	v_sub_f32_e32 v29, v27, v26
	v_mov_b32_e32 v31, v26
	v_pk_add_f32 v[26:27], v[26:27], v[28:29] neg_lo:[0,1] neg_hi:[0,1]
	v_cvt_f32_i32_e32 v24, v24
	v_pk_add_f32 v[26:27], v[26:27], v[30:31] neg_lo:[0,1] neg_hi:[0,1]
	v_cmp_neq_f32_e64 s[0:1], s8, v39
	v_add_f32_e32 v27, v34, v27
	v_add_f32_e32 v26, v26, v27
	v_add_f32_e32 v27, v29, v26
	v_mul_f32_e32 v31, v33, v27
	v_mul_f32_e32 v28, v32, v31
	v_sub_f32_e32 v29, v29, v27
	v_add_f32_e32 v36, v35, v31
	v_fma_f32 v30, v31, v32, -v28
	v_add_f32_e32 v34, v26, v29
	v_sub_f32_e32 v26, v36, v35
	v_fmac_f32_e32 v30, v31, v25
	v_sub_f32_e32 v25, v31, v26
	v_add_f32_e32 v26, v28, v30
	v_sub_f32_e32 v29, v27, v26
	v_mov_b32_e32 v31, v26
	v_pk_add_f32 v[26:27], v[26:27], v[28:29] neg_lo:[0,1] neg_hi:[0,1]
	s_nop 0
	v_pk_add_f32 v[26:27], v[26:27], v[30:31] neg_lo:[0,1] neg_hi:[0,1]
	s_nop 0
	v_add_f32_e32 v27, v34, v27
	v_add_f32_e32 v26, v26, v27
	v_add_f32_e32 v26, v29, v26
	v_mul_f32_e32 v26, v33, v26
	v_add_f32_e32 v25, v25, v26
	v_add_f32_e32 v26, v36, v25
	v_mul_f32_e32 v28, v26, v26
	v_sub_f32_e32 v29, v26, v36
	v_fmamk_f32 v30, v28, 0x3e9b6dac, v197
	v_sub_f32_e32 v29, v25, v29
	v_mul_f32_e32 v25, v26, v28
	v_fmaak_f32 v153, v28, v30, 0x3f2aaada
	v_ldexp_f32 v31, v29, 1
	v_pk_mul_f32 v[28:29], v[24:25], v[152:153]
	v_ldexp_f32 v27, v26, 1
	v_fma_f32 v26, v24, s75, -v28
	v_fmac_f32_e32 v26, 0xb102e308, v24
	v_pk_add_f32 v[24:25], v[28:29], v[26:27]
	v_mov_b32_e32 v30, v28
	v_sub_f32_e32 v34, v25, v27
	v_pk_add_f32 v[32:33], v[24:25], v[28:29] neg_lo:[0,1] neg_hi:[0,1]
	v_sub_f32_e32 v28, v29, v34
	v_add_f32_e32 v31, v31, v28
	v_pk_add_f32 v[28:29], v[24:25], v[30:31]
	v_mov_b32_e32 v27, v24
	v_mov_b32_e32 v33, v29
	v_pk_add_f32 v[36:37], v[26:27], v[32:33] neg_lo:[0,1] neg_hi:[0,1]
	v_pk_add_f32 v[26:27], v[26:27], v[32:33]
	v_mov_b32_e32 v35, v24
	v_pk_add_f32 v[32:33], v[26:27], v[24:25] op_sel:[1,0] op_sel_hi:[0,1] neg_lo:[0,1] neg_hi:[0,1]
	v_mov_b32_e32 v34, v31
	v_mov_b32_e32 v30, v29
	v_mov_b32_e32 v31, v27
	v_pk_mov_b32 v[24:25], v[24:25], v[32:33] op_sel:[1,0]
	v_pk_add_f32 v[28:29], v[28:29], v[32:33] op_sel_hi:[1,0] neg_lo:[0,1] neg_hi:[0,1]
	v_pk_add_f32 v[24:25], v[30:31], v[24:25] neg_lo:[0,1] neg_hi:[0,1]
	v_mov_b32_e32 v28, v36
	v_pk_add_f32 v[24:25], v[34:35], v[24:25] neg_lo:[0,1] neg_hi:[0,1]
	v_mov_b32_e32 v37, v27
	v_pk_add_f32 v[28:29], v[28:29], v[24:25]
	s_nop 0
	v_pk_add_f32 v[30:31], v[28:29], v[28:29] op_sel:[0,1] op_sel_hi:[1,0]
	s_nop 0
	v_pk_add_f32 v[26:27], v[26:27], v[30:31] op_sel:[1,0] op_sel_hi:[0,1]
	v_mov_b32_e32 v29, v26
	v_mov_b32_e32 v25, v30
	v_pk_add_f32 v[30:31], v[28:29], v[36:37] neg_lo:[0,1] neg_hi:[0,1]
	s_nop 0
	v_sub_f32_e32 v27, v28, v30
	v_pk_add_f32 v[24:25], v[24:25], v[30:31] neg_lo:[0,1] neg_hi:[0,1]
	v_sub_f32_e32 v27, v36, v27
	v_add_f32_e32 v24, v24, v27
	v_add_f32_e32 v24, v24, v25
	v_add_f32_e32 v24, v26, v24
	v_cndmask_b32_e64 v24, v200, v24, s[0:1]
	v_cmp_ngt_f32_e64 s[0:1], -1.0, v39
	s_nop 1
	v_cndmask_b32_e64 v24, v201, v24, s[0:1]
	v_cmp_neq_f32_e64 s[0:1], -1.0, v39
	s_nop 1
	v_cndmask_b32_e64 v24, v202, v24, s[0:1]
	v_cmp_lt_f32_e64 s[0:1], |v39|, s86
	s_nop 1
	v_cndmask_b32_e64 v24, v24, v39, s[0:1]
	v_add_f32_e32 v24, v38, v24
	s_cselect_b64 s[0:1], -1, 0
	s_cmp_eq_u32 s92, 6
	v_sub_f32_e32 v0, v0, v24
	s_cselect_b64 s[68:69], -1, 0
	s_cmp_eq_u32 s92, 5
	v_cndmask_b32_e64 v9, v9, v0, s[0:1]
	s_cselect_b64 s[0:1], -1, 0
	s_cmp_eq_u32 s92, 4
	v_cndmask_b32_e64 v7, v7, v0, s[0:1]
	s_cselect_b64 s[0:1], -1, 0
	s_cmp_eq_u32 s92, 3
	v_cndmask_b32_e64 v6, v6, v0, s[0:1]
	s_cselect_b64 s[0:1], -1, 0
	s_cmp_eq_u32 s92, 2
	v_cndmask_b32_e64 v5, v5, v0, s[0:1]
	s_cselect_b64 s[0:1], -1, 0
	s_cmp_eq_u32 s92, 1
	v_cndmask_b32_e64 v4, v4, v0, s[0:1]
	s_cselect_b64 s[0:1], -1, 0
	s_cmp_eq_u32 s92, 0
	v_cndmask_b32_e64 v3, v3, v0, s[0:1]
	s_cselect_b64 s[0:1], -1, 0
	s_add_u32 s92, s92, 1
	s_addc_u32 s93, s93, 0
	v_cndmask_b32_e64 v8, v8, v0, s[68:69]
	s_cmp_eq_u32 s92, 8
	v_cndmask_b32_e64 v2, v2, v0, s[0:1]
	s_cbranch_scc0 .LBB0_213
	ds_bpermute_b32 v14, v16, v0
	s_waitcnt lgkmcnt(0)
	s_barrier
	v_add_f32_e32 v14, v0, v14
	v_cndmask_b32_e64 v14, v14, v0, s[38:39]
	ds_bpermute_b32 v15, v17, v14
	s_waitcnt lgkmcnt(0)
	v_add_f32_e32 v15, v14, v15
	v_cndmask_b32_e64 v14, v15, v14, s[40:41]
	ds_bpermute_b32 v15, v18, v14
	s_waitcnt lgkmcnt(0)
	v_add_f32_e32 v15, v14, v15
	v_cndmask_b32_e64 v14, v15, v14, s[42:43]
	ds_bpermute_b32 v15, v19, v14
	s_waitcnt lgkmcnt(0)
	v_add_f32_e32 v15, v14, v15
	v_cndmask_b32_e64 v14, v15, v14, s[44:45]
	ds_bpermute_b32 v15, v20, v14
	s_waitcnt lgkmcnt(0)
	v_add_f32_e32 v15, v14, v15
	v_cndmask_b32_e64 v14, v15, v14, s[46:47]
	ds_bpermute_b32 v15, v21, v14
	s_waitcnt lgkmcnt(0)
	v_add_f32_e32 v15, v14, v15
	s_and_saveexec_b64 s[0:1], vcc
	s_cbranch_execz .LBB0_211
	ds_write_b32 v22, v15
	s_branch .LBB0_211

; DI float bflo(unsigned w) { return __uint_as_float(w << 16); }
; DI float bfhi(unsigned w) { return __uint_as_float(w & 0xffff0000u); }
; DI int tid_() { int t = threadIdx.x; asm volatile("" : "+v"(t)); return t; }
; DI float wave_sum(float v) { v += shx(v, 32); v += shx(v, 16); v += shx(v, 8); v += shx(v, 4); v += shx(v, 2); v += shx(v, 1); return v; }
; DI int bid_() { return (int)blockIdx.x; }
; DI void phase_post(const Params& p, int L) {
;     ...
;     const int tid = tid_(), wave = tid >> 6, lane = tid & 63;
;     const float lambda_init = 0.8f - 0.6f * __expf(-0.3f * (float)L);
;     const float s1 = wave_sum(p.in[11][j * 64 + lane] * p.in[12][j * 64 + lane]), s2 = wave_sum(p.in[13][j * 64 + lane] * p.in[14][j * 64 + lane]);
;     const float lam = expf(s1) - expf(s2) + lambda_init;
;     const bool isa = lane < 32; const int d0 = (lane & 7) * 16;
;     float nw[16];
;     { const float* src = isa ? (p.in[10] + j * 128 + d0) : (p.in[15] + j * 128 + d0); for (int e = 0; e < 16; ++e) nw[e] = src[e] * (isa ? 1.f : (1.f - lambda_init)); }
;     for (int row = bid_() * 8 + wave; row < MTOK; row += gridDim.x * 8) {
;         const bf16_t* pr = P + (size_t)row * PE;
;         float o[16];
;         if (isa) { const u32x4 a = *(const u32x4*)(pr + 1024 + 16 * lane), bq = *(const u32x4*)(pr + 1024 + 16 * lane + 8);
;             const unsigned uw[8] = {a.x, a.y, a.z, a.w, bq.x, bq.y, bq.z, bq.w};
;             for (int q = 0; q < 8; ++q) { o[2 * q] = bflo(uw[q]); o[2 * q + 1] = bfhi(uw[q]); } }
;         else { const int l2 = lane - 32;
;             const u32x4 a = *(const u32x4*)(pr + 16 * l2), bq = *(const u32x4*)(pr + 16 * l2 + 8), c = *(const u32x4*)(pr + 512 + 16 * l2), d = *(const u32x4*)(pr + 512 + 16 * l2 + 8);
.LBB0_610:
	s_or_b64 exec, exec, s[0:1]
	v_mov_b32_e32 v3, v194
	s_waitcnt lgkmcnt(0)
	s_barrier
	v_readlane_b32 s36, v250, 5
	v_and_b32_e32 v2, 63, v3
	v_lshl_or_b32 v0, s56, 5, v2
	v_lshlrev_b64 v[8:9], 2, v[0:1]
	v_readlane_b32 s42, v250, 11
	v_readlane_b32 s43, v250, 12
	v_readlane_b32 s44, v250, 13
	v_readlane_b32 s45, v250, 14
	v_lshl_add_u64 v[4:5], s[42:43], 0, v[8:9]
	global_load_dword v0, v[4:5], off
	v_lshl_add_u64 v[4:5], s[44:45], 0, v[8:9]
	global_load_dword v4, v[4:5], off
	v_mov_b32_e32 v7, v194
	v_readlane_b32 s46, v250, 15
	v_lshlrev_b32_e32 v7, 2, v7
	v_bitop3_b32 v7, v7, s29, v199 bitop3:0x6c
	v_readlane_b32 s47, v250, 16
	v_readlane_b32 s48, v250, 17
	v_readlane_b32 s49, v250, 18
	v_lshl_add_u64 v[10:11], s[46:47], 0, v[8:9]
	v_ashrrev_i32_e32 v6, 6, v3
	v_lshl_add_u64 v[8:9], s[48:49], 0, v[8:9]
	v_readlane_b32 s0, v250, 55
	v_readlane_b32 s37, v250, 6
	v_readlane_b32 s38, v250, 7
	v_readlane_b32 s39, v250, 8
	v_readlane_b32 s40, v250, 9
	v_readlane_b32 s41, v250, 10
	v_readlane_b32 s50, v250, 19
	v_readlane_b32 s51, v250, 20
	s_waitcnt vmcnt(0)
	v_mul_f32_e32 v5, v0, v4
	ds_bpermute_b32 v5, v7, v5
	s_waitcnt lgkmcnt(0)
	v_fmac_f32_e32 v5, v0, v4
	v_mov_b32_e32 v0, v194
	v_mov_b32_e32 v4, v194
	v_lshlrev_b32_e32 v0, 2, v0
	v_bitop3_b32 v0, v0, 64, v199 bitop3:0x6c
	ds_bpermute_b32 v0, v0, v5
	s_waitcnt lgkmcnt(0)
	v_add_f32_e32 v0, v5, v0
	v_lshlrev_b32_e32 v4, 2, v4
	v_bitop3_b32 v4, v4, 32, v199 bitop3:0x6c
	ds_bpermute_b32 v4, v4, v0
	s_waitcnt lgkmcnt(0)
	v_add_f32_e32 v0, v0, v4
	v_mov_b32_e32 v4, v194
	s_nop 0
	v_lshlrev_b32_e32 v4, 2, v4
	v_bitop3_b32 v4, v4, 16, v199 bitop3:0x6c
	ds_bpermute_b32 v4, v4, v0
	s_waitcnt lgkmcnt(0)
	v_add_f32_e32 v0, v0, v4
	v_mov_b32_e32 v4, v194
	s_nop 0
	v_lshlrev_b32_e32 v4, 2, v4
	v_bitop3_b32 v4, v4, 8, v199 bitop3:0x6c
	ds_bpermute_b32 v4, v4, v0
	s_waitcnt lgkmcnt(0)
	v_add_f32_e32 v4, v0, v4
	v_mov_b32_e32 v0, v194
	global_load_dword v7, v[8:9], off
	v_lshlrev_b32_e32 v0, 2, v0
	v_bitop3_b32 v0, v0, 4, v199 bitop3:0x6c
	ds_bpermute_b32 v5, v0, v4
	global_load_dword v0, v[10:11], off
	v_mov_b32_e32 v9, v194
	v_add_u32_e32 v10, s0, v6
	v_lshlrev_b32_e32 v9, 2, v9
	v_bitop3_b32 v9, v9, s29, v199 bitop3:0x6c
	s_mov_b32 s0, 0x8000
	v_cmp_gt_i32_e32 vcc, s0, v10
	s_waitcnt vmcnt(0)
	v_mul_f32_e32 v8, v0, v7
	ds_bpermute_b32 v8, v9, v8
	s_waitcnt lgkmcnt(0)
	v_fmac_f32_e32 v8, v0, v7
	v_mov_b32_e32 v0, v194
	v_mov_b32_e32 v7, v194
	v_lshlrev_b32_e32 v0, 2, v0
	v_bitop3_b32 v0, v0, 64, v199 bitop3:0x6c
	ds_bpermute_b32 v0, v0, v8
	s_waitcnt lgkmcnt(0)
	v_add_f32_e32 v0, v8, v0
	v_lshlrev_b32_e32 v7, 2, v7
	v_bitop3_b32 v7, v7, 32, v199 bitop3:0x6c
	ds_bpermute_b32 v7, v7, v0
	s_waitcnt lgkmcnt(0)
	v_add_f32_e32 v0, v0, v7
	v_mov_b32_e32 v7, v194
	s_nop 0
	v_lshlrev_b32_e32 v7, 2, v7
	v_bitop3_b32 v7, v7, 16, v199 bitop3:0x6c
	ds_bpermute_b32 v7, v7, v0
	s_waitcnt lgkmcnt(0)
	v_add_f32_e32 v0, v0, v7
	v_mov_b32_e32 v7, v194
	s_nop 0
	v_lshlrev_b32_e32 v7, 2, v7
	v_bitop3_b32 v7, v7, 8, v199 bitop3:0x6c
	ds_bpermute_b32 v7, v7, v0
	s_waitcnt lgkmcnt(0)
	v_add_f32_e32 v7, v0, v7
	v_mov_b32_e32 v0, v194
	s_nop 0
	v_lshlrev_b32_e32 v0, 2, v0
	v_bitop3_b32 v0, v0, 4, v199 bitop3:0x6c
	ds_bpermute_b32 v8, v0, v7
	s_and_saveexec_b64 s[0:1], vcc
	s_cbranch_execz .LBB0_619
	v_cvt_f32_u32_e32 v0, s56
	s_lshl_b32 s82, s56, 6
	s_mov_b32 s2, s56
	v_readlane_b32 s44, v250, 5
	v_mul_f32_e32 v0, 0xbe99999a, v0
	v_mul_f32_e32 v0, 0x3fb8aa3b, v0
	v_exp_f32_e32 v0, v0
	v_readlane_b32 s49, v250, 10
	v_readlane_b32 s59, v250, 20
	v_cmp_gt_u32_e64 s[40:41], 32, v2
	v_fmamk_f32 v6, v0, 0xbf19999a, v198
	v_readlane_b32 s48, v250, 9
	v_readlane_b32 s58, v250, 19
	v_mov_b32_e32 v0, s59
	v_mov_b32_e32 v11, s49
	v_cndmask_b32_e64 v13, v0, v11, s[40:41]
	v_mov_b32_e32 v0, s58
	v_mov_b32_e32 v11, s48
	v_cndmask_b32_e64 v12, v0, v11, s[40:41]
	v_lshlrev_b32_e32 v0, 6, v3
	v_lshl_add_u64 v[12:13], s[82:83], 2, v[12:13]
	v_and_b32_e32 v0, 0x1c0, v0
	v_lshl_add_u64 v[12:13], v[12:13], 0, v[0:1]
	global_load_dwordx4 v[24:27], v[12:13], off offset:48
	global_load_dwordx4 v[20:23], v[12:13], off offset:32
	global_load_dwordx4 v[16:19], v[12:13], off offset:16
	s_nop 0
	global_load_dwordx4 v[12:15], v[12:13], off
	v_sub_f32_e32 v9, 1.0, v6
	v_cndmask_b32_e64 v0, v9, 1.0, s[40:41]
	v_readlane_b32 s56, v250, 17
	s_mov_b32 s56, s2
	s_mov_b32 s2, 0x3fb8aa3b
	s_mov_b32 s3, 0xc2ce8ed0
	s_mov_b32 s10, 0x42b17218
	v_lshlrev_b32_e32 v30, 4, v2
	v_cmp_lt_u32_e64 s[38:39], 31, v2
	v_add_u32_e32 v32, 0xfffffe00, v30
	v_mov_b32_e32 v33, v1
	s_mov_b64 s[42:43], 0
	v_readlane_b32 s45, v250, 6
	v_readlane_b32 s46, v250, 7
	v_readlane_b32 s47, v250, 8
	v_readlane_b32 s50, v250, 11
	v_readlane_b32 s51, v250, 12
	v_readlane_b32 s52, v250, 13
	v_readlane_b32 s53, v250, 14
	v_readlane_b32 s54, v250, 15
	v_readlane_b32 s55, v250, 16
	v_readlane_b32 s57, v250, 18
	s_waitcnt vmcnt(3)
	v_pk_mul_f32 v[24:25], v[0:1], v[24:25] op_sel_hi:[0,1]
	s_waitcnt vmcnt(2)
	v_pk_mul_f32 v[20:21], v[0:1], v[20:21] op_sel_hi:[0,1]
	s_waitcnt vmcnt(1)
	v_pk_mul_f32 v[16:17], v[0:1], v[16:17] op_sel_hi:[0,1]
	s_waitcnt vmcnt(0)
	v_pk_mul_f32 v[12:13], v[0:1], v[12:13] op_sel_hi:[0,1]
	v_pk_mul_f32 v[14:15], v[0:1], v[14:15] op_sel_hi:[0,1]
	v_pk_mul_f32 v[18:19], v[0:1], v[18:19] op_sel_hi:[0,1]
	v_pk_mul_f32 v[22:23], v[0:1], v[22:23] op_sel_hi:[0,1]
	v_pk_mul_f32 v[26:27], v[0:1], v[26:27] op_sel_hi:[0,1]
	v_add_f32_e32 v0, v4, v5
	v_mul_f32_e32 v3, 0x3fb8aa3b, v0
	v_fma_f32 v4, v0, s2, -v3
	v_rndne_f32_e32 v5, v3
	v_fmac_f32_e32 v4, 0x32a5705f, v0
	v_sub_f32_e32 v3, v3, v5
	v_add_f32_e32 v3, v3, v4
	v_exp_f32_e32 v3, v3
	v_cvt_i32_f32_e32 v4, v5
	v_cmp_ngt_f32_e32 vcc, s3, v0
	v_ldexp_f32 v3, v3, v4
	s_nop 0
	v_cndmask_b32_e32 v3, 0, v3, vcc
	v_cmp_nlt_f32_e32 vcc, s10, v0
	s_nop 1
	v_cndmask_b32_e32 v0, v200, v3, vcc
	s_waitcnt lgkmcnt(0)
	v_add_f32_e32 v3, v7, v8
	v_mul_f32_e32 v4, 0x3fb8aa3b, v3
	v_fma_f32 v5, v3, s2, -v4
	v_rndne_f32_e32 v7, v4
	v_fmac_f32_e32 v5, 0x32a5705f, v3
	v_sub_f32_e32 v4, v4, v7
	v_add_f32_e32 v4, v4, v5
	v_exp_f32_e32 v4, v4
	v_cvt_i32_f32_e32 v5, v7
	v_cmp_ngt_f32_e32 vcc, s3, v3
	v_ldexp_f32 v4, v4, v5
	s_nop 0
	v_cndmask_b32_e32 v4, 0, v4, vcc
	v_cmp_nlt_f32_e32 vcc, s10, v3
	s_nop 1
	v_cndmask_b32_e32 v3, v200, v4, vcc
	v_sub_f32_e32 v0, v0, v3
	v_add_f32_e32 v28, v6, v0
	v_lshlrev_b32_e32 v0, 5, v2
	v_lshl_add_u64 v[34:35], s[24:25], 0, v[0:1]
	v_mov_b32_e32 v29, v28
	v_lshlrev_b64 v[112:113], 1, v[32:33]
	s_mov_b64 s[2:3], exec
	s_andn2_b64 exec, exec, s[38:39]
	v_lshlrev_b32_e32 v112, 1, v30
	v_mov_b32_e32 v113, 0
	v_add_u32_e32 v112, 0x800, v112
	s_mov_b64 exec, s[2:3]
	v_mov_b64_e32 v[114:115], s[4:5]
	s_nop 0
	v_mad_i64_i32 v[114:115], s[2:3], v10, s95, v[114:115]
	v_lshl_add_u64 v[116:117], v[114:115], 0, v[112:113]
	global_load_dwordx4 v[96:99], v[116:117], off
	global_load_dwordx4 v[100:103], v[116:117], off offset:16
	global_load_dwordx4 v[104:107], v[116:117], off offset:1024
	global_load_dwordx4 v[108:111], v[116:117], off offset:1040
	s_waitcnt vmcnt(0)
	s_branch .Lmy_post_top

; DI float bflo(unsigned w) { return __uint_as_float(w << 16); }
; DI float bfhi(unsigned w) { return __uint_as_float(w & 0xffff0000u); }
; DI float shx(float v, int m) { const int lane = tid_() & 63; return __builtin_bit_cast(float, __builtin_amdgcn_ds_bpermute((lane ^ m) << 2, __builtin_bit_cast(int, v))); }
; DI int bid_() { return (int)blockIdx.x; }
; DI void phase_post(const Params& p, int L) {
;     ...
;     for (int row = bid_() * 8 + wave; row < MTOK; row += gridDim.x * 8) {
;         const bf16_t* pr = P + (size_t)row * PE;
;         float o[16];
;         if (isa) { const u32x4 a = *(const u32x4*)(pr + 1024 + 16 * lane), bq = *(const u32x4*)(pr + 1024 + 16 * lane + 8);
;             const unsigned uw[8] = {a.x, a.y, a.z, a.w, bq.x, bq.y, bq.z, bq.w};
;             for (int q = 0; q < 8; ++q) { o[2 * q] = bflo(uw[q]); o[2 * q + 1] = bfhi(uw[q]); } }
;         else { const int l2 = lane - 32;
;             const u32x4 a = *(const u32x4*)(pr + 16 * l2), bq = *(const u32x4*)(pr + 16 * l2 + 8), c = *(const u32x4*)(pr + 512 + 16 * l2), d = *(const u32x4*)(pr + 512 + 16 * l2 + 8);
;             const unsigned u1[8] = {a.x, a.y, a.z, a.w, bq.x, bq.y, bq.z, bq.w}, u2[8] = {c.x, c.y, c.z, c.w, d.x, d.y, d.z, d.w};
;             for (int q = 0; q < 8; ++q) { o[2 * q] = bflo(u1[q]) - lam * bflo(u2[q]); o[2 * q + 1] = bfhi(u1[q]) - lam * bfhi(u2[q]); } }
;         float ss = 0.f; for (int e = 0; e < 16; ++e) ss += o[e] * o[e];
;         ss += shx(ss, 1); ss += shx(ss, 2); ss += shx(ss, 4);
;         const float rn = rsqrtf(ss * (1.f / 128.f) + EPS);
;         float g[16];
.LBB0_613:
	s_waitcnt vmcnt(2)
.Lmy_post_top:
	s_and_saveexec_b64 s[2:3], s[38:39]
	s_xor_b64 s[2:3], exec, s[2:3]
	s_cbranch_execz .LBB0_615
	v_lshlrev_b32_e32 v8, 16, v96
	v_and_b32_e32 v9, 0xffff0000, v96
	v_lshlrev_b32_e32 v36, 16, v104
	v_and_b32_e32 v37, 0xffff0000, v104
	v_pk_fma_f32 v[36:37], v[28:29], v[36:37], v[8:9] neg_lo:[1,0,0] neg_hi:[1,0,0]
	v_lshlrev_b32_e32 v8, 16, v97
	v_and_b32_e32 v9, 0xffff0000, v97
	v_lshlrev_b32_e32 v38, 16, v105
	v_and_b32_e32 v39, 0xffff0000, v105
	v_pk_fma_f32 v[38:39], v[28:29], v[38:39], v[8:9] neg_lo:[1,0,0] neg_hi:[1,0,0]
	v_lshlrev_b32_e32 v8, 16, v98
	v_and_b32_e32 v9, 0xffff0000, v98
	v_lshlrev_b32_e32 v40, 16, v106
	v_and_b32_e32 v41, 0xffff0000, v106
	v_pk_fma_f32 v[40:41], v[28:29], v[40:41], v[8:9] neg_lo:[1,0,0] neg_hi:[1,0,0]
	v_lshlrev_b32_e32 v8, 16, v99
	v_and_b32_e32 v9, 0xffff0000, v99
	v_lshlrev_b32_e32 v42, 16, v107
	v_and_b32_e32 v43, 0xffff0000, v107
	v_pk_fma_f32 v[42:43], v[28:29], v[42:43], v[8:9] neg_lo:[1,0,0] neg_hi:[1,0,0]
	v_lshlrev_b32_e32 v8, 16, v100
	v_and_b32_e32 v9, 0xffff0000, v100
	v_lshlrev_b32_e32 v44, 16, v108
	v_and_b32_e32 v45, 0xffff0000, v108
	v_pk_fma_f32 v[44:45], v[28:29], v[44:45], v[8:9] neg_lo:[1,0,0] neg_hi:[1,0,0]
	v_lshlrev_b32_e32 v4, 16, v101
	v_and_b32_e32 v5, 0xffff0000, v101
	v_lshlrev_b32_e32 v8, 16, v109
	v_and_b32_e32 v9, 0xffff0000, v109
	v_pk_fma_f32 v[46:47], v[28:29], v[8:9], v[4:5] neg_lo:[1,0,0] neg_hi:[1,0,0]
	v_lshlrev_b32_e32 v4, 16, v102
	v_and_b32_e32 v5, 0xffff0000, v102
	v_lshlrev_b32_e32 v8, 16, v110
	v_and_b32_e32 v9, 0xffff0000, v110
	v_pk_fma_f32 v[48:49], v[28:29], v[8:9], v[4:5] neg_lo:[1,0,0] neg_hi:[1,0,0]
	v_lshlrev_b32_e32 v4, 16, v103
	v_and_b32_e32 v5, 0xffff0000, v103
	v_lshlrev_b32_e32 v6, 16, v111
	v_and_b32_e32 v7, 0xffff0000, v111
	v_pk_fma_f32 v[50:51], v[28:29], v[6:7], v[4:5] neg_lo:[1,0,0] neg_hi:[1,0,0]
.LBB0_615:
	s_andn2_saveexec_b64 s[2:3], s[2:3]
	s_cbranch_execz .LBB0_617
	v_lshlrev_b32_e32 v36, 16, v96
	v_and_b32_e32 v37, 0xffff0000, v96
	v_lshlrev_b32_e32 v38, 16, v97
	v_and_b32_e32 v39, 0xffff0000, v97
	v_lshlrev_b32_e32 v40, 16, v98
	v_and_b32_e32 v41, 0xffff0000, v98
	v_lshlrev_b32_e32 v42, 16, v99
	v_and_b32_e32 v43, 0xffff0000, v99
	v_lshlrev_b32_e32 v44, 16, v100
	v_and_b32_e32 v45, 0xffff0000, v100
	v_lshlrev_b32_e32 v46, 16, v101
	v_and_b32_e32 v47, 0xffff0000, v101
	v_lshlrev_b32_e32 v48, 16, v102
	v_and_b32_e32 v49, 0xffff0000, v102
	v_lshlrev_b32_e32 v50, 16, v103
	v_and_b32_e32 v51, 0xffff0000, v103
	v_mov_b32_e32 v88, v108
	v_mov_b32_e32 v89, v109
	v_mov_b32_e32 v90, v110
	v_mov_b32_e32 v91, v111
	v_mov_b32_e32 v92, v104
	v_mov_b32_e32 v93, v105
	v_mov_b32_e32 v94, v106
	v_mov_b32_e32 v95, v107
.LBB0_617:
	s_or_b64 exec, exec, s[2:3]
	v_add_u32_e32 v118, s71, v10
	v_min_i32_e32 v118, 0x7fff, v118
	v_mov_b64_e32 v[114:115], s[4:5]
	s_nop 0
	v_mad_i64_i32 v[114:115], s[2:3], v118, s95, v[114:115]
	v_lshl_add_u64 v[116:117], v[114:115], 0, v[112:113]
	global_load_dwordx4 v[96:99], v[116:117], off
	global_load_dwordx4 v[100:103], v[116:117], off offset:16
	global_load_dwordx4 v[104:107], v[116:117], off offset:1024
	global_load_dwordx4 v[108:111], v[116:117], off offset:1040
	v_mul_f32_e32 v0, v37, v37
	v_fmac_f32_e32 v0, v36, v36
	v_fmac_f32_e32 v0, v38, v38
	v_fmac_f32_e32 v0, v39, v39
	v_fmac_f32_e32 v0, v40, v40
	v_fmac_f32_e32 v0, v41, v41
	v_fmac_f32_e32 v0, v42, v42
	v_fmac_f32_e32 v0, v43, v43
	v_pk_mul_f32 v[52:53], v[44:45], v[44:45]
	v_pk_mul_f32 v[8:9], v[46:47], v[46:47]
	v_add_f32_e32 v0, v52, v0
	v_add_f32_e32 v0, v53, v0
	v_add_f32_e32 v0, v8, v0
	v_pk_mul_f32 v[6:7], v[48:49], v[48:49]
	v_add_f32_e32 v0, v9, v0
	v_add_f32_e32 v0, v6, v0
	v_pk_mul_f32 v[4:5], v[50:51], v[50:51]
	v_add_f32_e32 v0, v7, v0
	v_add_f32_e32 v0, v4, v0
	v_mov_b32_e32 v4, v194
	v_add_f32_e32 v0, v5, v0
	v_lshlrev_b32_e32 v4, 2, v4
	v_bitop3_b32 v4, v4, 4, v199 bitop3:0x6c
	ds_bpermute_b32 v4, v4, v0
	v_mov_b32_e32 v62, 1.0
	v_mov_b32_e32 v63, 1.0
	v_mov_b32_e32 v8, 1.0
	v_mov_b32_e32 v9, 1.0
	s_waitcnt lgkmcnt(0)
	v_add_f32_e32 v0, v0, v4
	v_mov_b32_e32 v4, v194
	v_mov_b32_e32 v54, 1.0
	v_lshlrev_b32_e32 v4, 2, v4
	v_bitop3_b32 v4, v4, 8, v199 bitop3:0x6c
	ds_bpermute_b32 v4, v4, v0
	v_mov_b32_e32 v55, 1.0
	v_mov_b32_e32 v6, 1.0
	v_mov_b32_e32 v7, 1.0
	v_mov_b32_e32 v56, 1.0
	s_waitcnt lgkmcnt(0)
	v_add_f32_e32 v11, v0, v4
	v_mov_b32_e32 v0, v194
	v_mov_b32_e32 v57, 1.0
	v_lshlrev_b32_e32 v0, 2, v0
	v_bitop3_b32 v0, v0, 16, v199 bitop3:0x6c
	ds_bpermute_b32 v31, v0, v11
	v_mov_b32_e32 v58, 1.0
	v_mov_b32_e32 v59, 1.0
	v_mov_b32_e32 v60, 1.0
	v_mov_b32_e32 v61, 1.0
	v_mov_b32_e32 v4, 1.0
	v_mov_b32_e32 v5, 1.0
	s_and_saveexec_b64 s[44:45], s[40:41]
	s_cbranch_execz .LBB0_612
; DI float bflo(unsigned w) { return __uint_as_float(w << 16); }
; DI float bfhi(unsigned w) { return __uint_as_float(w & 0xffff0000u); }
; DI float sigmoidf_(float x) { return 1.f / (1.f + __expf(-x)); }
; DI void phase_post(const Params& p, int L) {
;     ...
;         if (isa) { const u32x4 a = *(const u32x4*)(pr + 1536 + 16 * lane), bq = *(const u32x4*)(pr + 1536 + 16 * lane + 8);
;             const unsigned uw[8] = {a.x, a.y, a.z, a.w, bq.x, bq.y, bq.z, bq.w};
;             for (int q = 0; q < 8; ++q) { const float z0 = bflo(uw[q]), z1 = bfhi(uw[q]); g[2 * q] = z0 * sigmoidf_(z0); g[2 * q + 1] = z1 * sigmoidf_(z1); } }
	v_mov_b32_e32 v2, v88
	v_mov_b32_e32 v3, v89
	v_mov_b32_e32 v4, v90
	v_mov_b32_e32 v5, v91
	v_mov_b32_e32 v6, v92
	v_mov_b32_e32 v7, v93
	v_mov_b32_e32 v8, v94
	v_mov_b32_e32 v9, v95
	v_lshlrev_b32_e32 v53, 16, v6
	v_and_b32_e32 v52, 0xffff0000, v6
	v_mul_f32_e32 v0, 0xbfb8aa3b, v53
	v_exp_f32_e32 v55, v0
	v_mul_f32_e32 v0, 0xbfb8aa3b, v52
	v_exp_f32_e32 v54, v0
	s_nop 0
	v_pk_add_f32 v[54:55], v[54:55], 1.0 op_sel_hi:[1,0]
	s_nop 0
	v_div_scale_f32 v0, s[2:3], v55, v55, 1.0
	v_rcp_f32_e32 v6, v0
	s_nop 0
	v_fma_f32 v56, -v0, v6, 1.0
	v_fmac_f32_e32 v6, v56, v6
	v_div_scale_f32 v56, vcc, 1.0, v55, 1.0
	v_mul_f32_e32 v57, v56, v6
	v_fma_f32 v58, -v0, v57, v56
	v_fmac_f32_e32 v57, v58, v6
	v_fma_f32 v0, -v0, v57, v56
	v_div_fmas_f32 v0, v0, v6, v57
	v_div_fixup_f32 v55, v0, v55, 1.0
	v_div_scale_f32 v0, s[2:3], v54, v54, 1.0
	v_rcp_f32_e32 v6, v0
	s_nop 0
	v_fma_f32 v56, -v0, v6, 1.0
	v_fmac_f32_e32 v6, v56, v6
	v_div_scale_f32 v56, vcc, 1.0, v54, 1.0
	v_mul_f32_e32 v57, v56, v6
	v_fma_f32 v58, -v0, v57, v56
	v_fmac_f32_e32 v57, v58, v6
	v_fma_f32 v0, -v0, v57, v56
	v_div_fmas_f32 v0, v0, v6, v57
	v_and_b32_e32 v6, 0xffff0000, v7
	v_lshlrev_b32_e32 v7, 16, v7
	v_div_fixup_f32 v54, v0, v54, 1.0
	v_mul_f32_e32 v0, 0xbfb8aa3b, v7
	v_pk_mul_f32 v[52:53], v[54:55], v[52:53]
	v_exp_f32_e32 v55, v0
	v_mul_f32_e32 v0, 0xbfb8aa3b, v6
	v_exp_f32_e32 v54, v0
	s_nop 0
	v_pk_add_f32 v[54:55], v[54:55], 1.0 op_sel_hi:[1,0]
	s_nop 0
	v_div_scale_f32 v0, s[2:3], v55, v55, 1.0
	v_rcp_f32_e32 v56, v0
	s_nop 0
	v_fma_f32 v57, -v0, v56, 1.0
	v_fmac_f32_e32 v56, v57, v56
	v_div_scale_f32 v57, vcc, 1.0, v55, 1.0
	v_mul_f32_e32 v58, v57, v56
	v_fma_f32 v59, -v0, v58, v57
	v_fmac_f32_e32 v58, v59, v56
	v_fma_f32 v0, -v0, v58, v57
	v_div_fmas_f32 v0, v0, v56, v58
	v_div_fixup_f32 v55, v0, v55, 1.0
	v_div_scale_f32 v0, s[2:3], v54, v54, 1.0
	v_rcp_f32_e32 v56, v0
	s_nop 0
	v_fma_f32 v57, -v0, v56, 1.0
	v_fmac_f32_e32 v56, v57, v56
	v_div_scale_f32 v57, vcc, 1.0, v54, 1.0
	v_mul_f32_e32 v58, v57, v56
	v_fma_f32 v59, -v0, v58, v57
	v_fmac_f32_e32 v58, v59, v56
	v_fma_f32 v0, -v0, v58, v57
	v_div_fmas_f32 v0, v0, v56, v58
	v_div_fixup_f32 v54, v0, v54, 1.0
	v_pk_mul_f32 v[6:7], v[54:55], v[6:7]
	v_lshlrev_b32_e32 v55, 16, v8
	v_and_b32_e32 v54, 0xffff0000, v8
	v_mul_f32_e32 v0, 0xbfb8aa3b, v55
	v_exp_f32_e32 v57, v0
	v_mul_f32_e32 v0, 0xbfb8aa3b, v54
	v_exp_f32_e32 v56, v0
	s_nop 0
	v_pk_add_f32 v[56:57], v[56:57], 1.0 op_sel_hi:[1,0]
	s_nop 0
	v_div_scale_f32 v0, s[2:3], v57, v57, 1.0
	v_rcp_f32_e32 v8, v0
	s_nop 0
	v_fma_f32 v58, -v0, v8, 1.0
	v_fmac_f32_e32 v8, v58, v8
	v_div_scale_f32 v58, vcc, 1.0, v57, 1.0
	v_mul_f32_e32 v59, v58, v8
	v_fma_f32 v60, -v0, v59, v58
	v_fmac_f32_e32 v59, v60, v8
	v_fma_f32 v0, -v0, v59, v58
	v_div_fmas_f32 v0, v0, v8, v59
	v_div_fixup_f32 v57, v0, v57, 1.0
	v_div_scale_f32 v0, s[2:3], v56, v56, 1.0
	v_rcp_f32_e32 v8, v0
	s_nop 0
	v_fma_f32 v58, -v0, v8, 1.0
	v_fmac_f32_e32 v8, v58, v8
	v_div_scale_f32 v58, vcc, 1.0, v56, 1.0
	v_mul_f32_e32 v59, v58, v8
	v_fma_f32 v60, -v0, v59, v58
	v_fmac_f32_e32 v59, v60, v8
	v_fma_f32 v0, -v0, v59, v58
	v_div_fmas_f32 v0, v0, v8, v59
	v_and_b32_e32 v8, 0xffff0000, v9
	v_lshlrev_b32_e32 v9, 16, v9
	v_div_fixup_f32 v56, v0, v56, 1.0
	v_mul_f32_e32 v0, 0xbfb8aa3b, v9
	v_pk_mul_f32 v[54:55], v[56:57], v[54:55]
	v_exp_f32_e32 v57, v0
	v_mul_f32_e32 v0, 0xbfb8aa3b, v8
	v_exp_f32_e32 v56, v0
	s_nop 0
	v_pk_add_f32 v[56:57], v[56:57], 1.0 op_sel_hi:[1,0]
	s_nop 0
	v_div_scale_f32 v0, s[2:3], v57, v57, 1.0
	v_rcp_f32_e32 v58, v0
	s_nop 0
	v_fma_f32 v59, -v0, v58, 1.0
	v_fmac_f32_e32 v58, v59, v58
	v_div_scale_f32 v59, vcc, 1.0, v57, 1.0
	v_mul_f32_e32 v60, v59, v58
	v_fma_f32 v61, -v0, v60, v59
	v_fmac_f32_e32 v60, v61, v58
	v_fma_f32 v0, -v0, v60, v59
	v_div_fmas_f32 v0, v0, v58, v60
	v_div_fixup_f32 v57, v0, v57, 1.0
	v_div_scale_f32 v0, s[2:3], v56, v56, 1.0
	v_rcp_f32_e32 v58, v0
	s_nop 0
	v_fma_f32 v59, -v0, v58, 1.0
	v_fmac_f32_e32 v58, v59, v58
	v_div_scale_f32 v59, vcc, 1.0, v56, 1.0
	v_mul_f32_e32 v60, v59, v58
	v_fma_f32 v61, -v0, v60, v59
	v_fmac_f32_e32 v60, v61, v58
	v_fma_f32 v0, -v0, v60, v59
	v_div_fmas_f32 v0, v0, v58, v60
	v_div_fixup_f32 v56, v0, v56, 1.0
	v_pk_mul_f32 v[8:9], v[56:57], v[8:9]
; DI float bflo(unsigned w) { return __uint_as_float(w << 16); }
; DI float bfhi(unsigned w) { return __uint_as_float(w & 0xffff0000u); }
; DI float sigmoidf_(float x) { return 1.f / (1.f + __expf(-x)); }
; DI void phase_post(const Params& p, int L) {
;     ...
;         if (isa) { const u32x4 a = *(const u32x4*)(pr + 1536 + 16 * lane), bq = *(const u32x4*)(pr + 1536 + 16 * lane + 8);
;             const unsigned uw[8] = {a.x, a.y, a.z, a.w, bq.x, bq.y, bq.z, bq.w};
;             for (int q = 0; q < 8; ++q) { const float z0 = bflo(uw[q]), z1 = bfhi(uw[q]); g[2 * q] = z0 * sigmoidf_(z0); g[2 * q + 1] = z1 * sigmoidf_(z1); } }
;         else for (int e = 0; e < 16; ++e) g[e] = 1.f;
;         for (int e = 0; e < 16; ++e) o[e] = o[e] * rn * nw[e] * g[e];
	v_lshlrev_b32_e32 v56, 16, v2
	v_and_b32_e32 v57, 0xffff0000, v2
	v_mul_f32_e32 v0, 0xbfb8aa3b, v56
	v_exp_f32_e32 v58, v0
	v_mul_f32_e32 v0, 0xbfb8aa3b, v57
	v_exp_f32_e32 v59, v0
	s_nop 0
	v_pk_add_f32 v[58:59], v[58:59], 1.0 op_sel_hi:[1,0]
	s_nop 0
	v_div_scale_f32 v0, s[2:3], v59, v59, 1.0
	v_rcp_f32_e32 v2, v0
	s_nop 0
	v_fma_f32 v60, -v0, v2, 1.0
	v_fmac_f32_e32 v2, v60, v2
	v_div_scale_f32 v60, vcc, 1.0, v59, 1.0
	v_mul_f32_e32 v61, v60, v2
	v_fma_f32 v62, -v0, v61, v60
	v_fmac_f32_e32 v61, v62, v2
	v_fma_f32 v0, -v0, v61, v60
	v_div_fmas_f32 v0, v0, v2, v61
	v_div_fixup_f32 v59, v0, v59, 1.0
	v_div_scale_f32 v0, s[2:3], v58, v58, 1.0
	v_rcp_f32_e32 v2, v0
	s_nop 0
	v_fma_f32 v60, -v0, v2, 1.0
	v_fmac_f32_e32 v2, v60, v2
	v_div_scale_f32 v60, vcc, 1.0, v58, 1.0
	v_mul_f32_e32 v61, v60, v2
	v_fma_f32 v62, -v0, v61, v60
	v_fmac_f32_e32 v61, v62, v2
	v_fma_f32 v0, -v0, v61, v60
	v_div_fmas_f32 v0, v0, v2, v61
	v_lshlrev_b32_e32 v2, 16, v3
	v_div_fixup_f32 v58, v0, v58, 1.0
	v_and_b32_e32 v3, 0xffff0000, v3
	v_mul_f32_e32 v0, 0xbfb8aa3b, v2
	v_pk_mul_f32 v[56:57], v[58:59], v[56:57]
	v_exp_f32_e32 v58, v0
	v_mul_f32_e32 v0, 0xbfb8aa3b, v3
	v_exp_f32_e32 v59, v0
	s_nop 0
	v_pk_add_f32 v[58:59], v[58:59], 1.0 op_sel_hi:[1,0]
	s_nop 0
	v_div_scale_f32 v0, s[2:3], v59, v59, 1.0
	v_rcp_f32_e32 v60, v0
	s_nop 0
	v_fma_f32 v61, -v0, v60, 1.0
	v_fmac_f32_e32 v60, v61, v60
	v_div_scale_f32 v61, vcc, 1.0, v59, 1.0
	v_mul_f32_e32 v62, v61, v60
	v_fma_f32 v63, -v0, v62, v61
	v_fmac_f32_e32 v62, v63, v60
	v_fma_f32 v0, -v0, v62, v61
	v_div_fmas_f32 v0, v0, v60, v62
	v_div_fixup_f32 v59, v0, v59, 1.0
	v_div_scale_f32 v0, s[2:3], v58, v58, 1.0
	v_rcp_f32_e32 v60, v0
	s_nop 0
	v_fma_f32 v61, -v0, v60, 1.0
	v_fmac_f32_e32 v60, v61, v60
	v_div_scale_f32 v61, vcc, 1.0, v58, 1.0
	v_mul_f32_e32 v62, v61, v60
	v_fma_f32 v63, -v0, v62, v61
	v_fmac_f32_e32 v62, v63, v60
	v_fma_f32 v0, -v0, v62, v61
	v_div_fmas_f32 v0, v0, v60, v62
	v_div_fixup_f32 v58, v0, v58, 1.0
	v_pk_mul_f32 v[58:59], v[58:59], v[2:3]
	v_lshlrev_b32_e32 v2, 16, v4
	v_and_b32_e32 v3, 0xffff0000, v4
	v_mul_f32_e32 v0, 0xbfb8aa3b, v2
	v_exp_f32_e32 v60, v0
	v_mul_f32_e32 v0, 0xbfb8aa3b, v3
	v_exp_f32_e32 v61, v0
	s_nop 0
	v_pk_add_f32 v[60:61], v[60:61], 1.0 op_sel_hi:[1,0]
	s_nop 0
	v_div_scale_f32 v0, s[2:3], v61, v61, 1.0
	v_rcp_f32_e32 v4, v0
	s_nop 0
	v_fma_f32 v62, -v0, v4, 1.0
	v_fmac_f32_e32 v4, v62, v4
	v_div_scale_f32 v62, vcc, 1.0, v61, 1.0
	v_mul_f32_e32 v63, v62, v4
	v_fma_f32 v64, -v0, v63, v62
	v_fmac_f32_e32 v63, v64, v4
	v_fma_f32 v0, -v0, v63, v62
	v_div_fmas_f32 v0, v0, v4, v63
	v_div_fixup_f32 v61, v0, v61, 1.0
	v_div_scale_f32 v0, s[2:3], v60, v60, 1.0
	v_rcp_f32_e32 v4, v0
	s_nop 0
	v_fma_f32 v62, -v0, v4, 1.0
	v_fmac_f32_e32 v4, v62, v4
	v_div_scale_f32 v62, vcc, 1.0, v60, 1.0
	v_mul_f32_e32 v63, v62, v4
	v_fma_f32 v64, -v0, v63, v62
	v_fmac_f32_e32 v63, v64, v4
	v_fma_f32 v0, -v0, v63, v62
	v_div_fmas_f32 v0, v0, v4, v63
	v_div_fixup_f32 v60, v0, v60, 1.0
	v_pk_mul_f32 v[60:61], v[60:61], v[2:3]
	v_lshlrev_b32_e32 v2, 16, v5
	v_and_b32_e32 v3, 0xffff0000, v5
	v_mul_f32_e32 v0, 0xbfb8aa3b, v2
	v_exp_f32_e32 v4, v0
	v_mul_f32_e32 v0, 0xbfb8aa3b, v3
	v_exp_f32_e32 v5, v0
	s_nop 0
	v_pk_add_f32 v[4:5], v[4:5], 1.0 op_sel_hi:[1,0]
	s_nop 0
	v_div_scale_f32 v0, s[2:3], v5, v5, 1.0
	v_rcp_f32_e32 v62, v0
	s_nop 0
	v_fma_f32 v63, -v0, v62, 1.0
	v_fmac_f32_e32 v62, v63, v62
	v_div_scale_f32 v63, vcc, 1.0, v5, 1.0
	v_mul_f32_e32 v64, v63, v62
	v_fma_f32 v65, -v0, v64, v63
	v_fmac_f32_e32 v64, v65, v62
	v_fma_f32 v0, -v0, v64, v63
	v_div_fmas_f32 v0, v0, v62, v64
	v_div_fixup_f32 v5, v0, v5, 1.0
	v_div_scale_f32 v0, s[2:3], v4, v4, 1.0
	v_rcp_f32_e32 v62, v0
	s_nop 0
	v_fma_f32 v63, -v0, v62, 1.0
	v_fmac_f32_e32 v62, v63, v62
	v_div_scale_f32 v63, vcc, 1.0, v4, 1.0
	v_mul_f32_e32 v64, v63, v62
	v_fma_f32 v65, -v0, v64, v63
	v_fmac_f32_e32 v64, v65, v62
	v_fma_f32 v0, -v0, v64, v63
	v_div_fmas_f32 v0, v0, v62, v64
	v_div_fixup_f32 v4, v0, v4, 1.0
	v_pk_mul_f32 v[4:5], v[4:5], v[2:3]
	v_mov_b32_e32 v62, v9
	v_mov_b32_e32 v63, v8
	v_mov_b32_e32 v8, v55
	v_mov_b32_e32 v9, v54
	v_mov_b32_e32 v54, v7
	v_mov_b32_e32 v55, v6
	v_mov_b32_e32 v6, v53
	v_mov_b32_e32 v7, v52
	s_branch .LBB0_612
